# base19 + LN2 row-loop latch: waits for the prefetched row count the row's 12/16 younger stores instead of draining them
# speedup vs baseline: 1.0092x; 1.0038x over previous
; #define LAS __attribute__((address_space(3)))
; __device__ __forceinline__ unsigned cvt_pk_bf16(float lo, float hi) { unsigned r; asm volatile("v_cvt_pk_bf16_f32 %0, %1, %2" : "=v"(r) : "v"(lo), "v"(hi)); return r; }
; __device__ __forceinline__ unsigned pk4c_fp8(f32x4 v) { return pk4_fp8(fminf(fmaxf(v[0], -448.f), 448.f), fminf(fmaxf(v[1], -448.f), 448.f), fminf(fmaxf(v[2], -448.f), 448.f), fminf(fmaxf(v[3], -448.f), 448.f)); }
; __device__ __forceinline__ void phase_ln2(const Args& a, LAS unsigned char* lds, const WCtx& w, int l, int nrows) {
;     ...
;         if (nrow < r1) { row_load(X + (size_t)nrow * 1024, w.lane, xn); nslot = SLOT[(size_t)nrow * 16 + (w.lane & 15)]; }
;         asm volatile("" ::: "memory");
;         const LAS float* bv = BV + ((row_batch(row) != b_lo) ? 3 * 1024 : 0);
; #pragma unroll
;         for (int j = 0; j < 4; ++j) x[j] = x[j] * ALPHA + *(const LAS f32x4*)(bv + 4 * w.lane + 256 * j) * mo[j];
;         float mean, rstd; ln_stats(x, mean, rstd);
; #pragma unroll
;         for (int j = 0; j < 4; ++j) x[j] = (x[j] - mean) * rstd * *(const LAS f32x4*)(LNG + 4 * w.lane + 256 * j) + *(const LAS f32x4*)(LNB + 4 * w.lane + 256 * j);
;         if (l == DEPTH - 1) row_store(a.out + (size_t)row * 1024, w.lane, x);
;         else { row_store(X + (size_t)row * 1024, w.lane, x);
;             ln_stats(x, mean, rstd); bf16* hrow = H + (size_t)row * 1024;
; #pragma unroll
;             for (int j = 0; j < 4; ++j) { const f32x4 sh = *(const LAS f32x4*)(bv + 1024 + 4 * w.lane + 256 * j), sc = *(const LAS f32x4*)(bv + 2048 + 4 * w.lane + 256 * j);
;                 const f32x4 hv = (x[j] - mean) * rstd * (sc + 1.0f) + sh;
;                 v2u wv; wv.x = cvt_pk_bf16(hv[0], hv[1]); wv.y = cvt_pk_bf16(hv[2], hv[3]); *((v2u*)hrow + w.lane + 64 * j) = wv;
;                 ((unsigned*)(a.ws + WS_H8 + (size_t)row * 1024))[w.lane + 64 * j] = pk4c_fp8(hv); } }
; #pragma unroll
;         for (int j = 0; j < 4; ++j) x[j] = xn[j];
;         myslot = nslot; row = nrow;
.Lm_latch12:
	s_andn2_b64 vcc, exec, s[6:7]
	s_mov_b32 s4, s2
	s_waitcnt vmcnt(16)
	v_mov_b32_e32 v30, v14
	v_mov_b32_e32 v31, v15
	v_mov_b32_e32 v32, v16
	v_mov_b32_e32 v33, v17
	s_waitcnt vmcnt(15)
	v_mov_b32_e32 v26, v10
	v_mov_b32_e32 v27, v11
	v_mov_b32_e32 v28, v12
	v_mov_b32_e32 v29, v13
	s_waitcnt vmcnt(14)
	v_mov_b32_e32 v22, v6
	v_mov_b32_e32 v23, v7
	v_mov_b32_e32 v24, v8
	v_mov_b32_e32 v25, v9
	s_waitcnt vmcnt(13)
	v_mov_b32_e32 v18, v2
	v_mov_b32_e32 v19, v3
	v_mov_b32_e32 v20, v4
	v_mov_b32_e32 v21, v5
	s_cbranch_vccz .LBB0_2571
	s_waitcnt vmcnt(12)
	s_branch .Lm_hdr
.Lm_latch16:
	s_andn2_b64 vcc, exec, s[6:7]
	s_mov_b32 s4, s2
	s_waitcnt vmcnt(20)
	v_mov_b32_e32 v30, v14
	v_mov_b32_e32 v31, v15
	v_mov_b32_e32 v32, v16
	v_mov_b32_e32 v33, v17
	s_waitcnt vmcnt(19)
	v_mov_b32_e32 v26, v10
	v_mov_b32_e32 v27, v11
	v_mov_b32_e32 v28, v12
	v_mov_b32_e32 v29, v13
	s_waitcnt vmcnt(18)
	v_mov_b32_e32 v22, v6
	v_mov_b32_e32 v23, v7
	v_mov_b32_e32 v24, v8
	v_mov_b32_e32 v25, v9
	s_waitcnt vmcnt(17)
	v_mov_b32_e32 v18, v2
	v_mov_b32_e32 v19, v3
	v_mov_b32_e32 v20, v4
	v_mov_b32_e32 v21, v5
	s_cbranch_vccz .LBB0_2571
	s_waitcnt vmcnt(16)
	s_branch .Lm_hdr

; __device__ __forceinline__ void phase_ln2(const Args& a, LAS unsigned char* lds, const WCtx& w, int l, int nrows) {
;     ...
;     while (row < r1) {
;         const int nrow = row + NWAVES; f32x4 xn[4]; int nslot = -1;
; #pragma unroll
;         for (int j = 0; j < 4; ++j) xn[j] = (f32x4){0.f, 0.f, 0.f, 0.f};
;         f32x4 mo[4];
; #pragma unroll
;         for (int j = 0; j < 4; ++j) mo[j] = (f32x4){0.f, 0.f, 0.f, 0.f};
;         const int b = row < ML ? (row >> 11) : ((row - ML) >> 8);
;         unsigned m = (unsigned)(__ballot(myslot >= 0) & 0xFFFFull);
;         while (m) {
.Lm_hdr:
	v_cmp_lt_i32_e32 vcc, -1, v69
	s_and_b32 s5, vcc_lo, 0xffff
	s_cmp_eq_u32 s5, 0
	s_cbranch_scc1 .LBB0_2563
	s_cmp_lt_i32 s4, 0x8000
	s_cselect_b64 s[0:1], -1, 0
	s_add_i32 s2, s4, 0xffff8000
	s_lshr_b32 s2, s2, 3
	s_and_b32 s2, s2, 0x1fffffe0
	s_ashr_i32 s3, s4, 3
	v_mov_b32_e32 v66, 0
	s_add_i32 s2, s2, 0x10000
	s_and_b32 s3, s3, 0xffffff00
	v_mov_b32_e32 v67, v66
	v_mov_b32_e32 v64, v66
	v_mov_b32_e32 v65, v66
	v_mov_b32_e32 v62, v66
	v_mov_b32_e32 v63, v66
	v_mov_b32_e32 v60, v66
	v_mov_b32_e32 v61, v66
	v_mov_b32_e32 v58, v66
	v_mov_b32_e32 v59, v66
	v_mov_b32_e32 v56, v66
	v_mov_b32_e32 v57, v66
	v_mov_b32_e32 v54, v66
	v_mov_b32_e32 v55, v66
	v_mov_b32_e32 v52, v66
	v_mov_b32_e32 v53, v66
	s_branch .LBB0_2557

; #define LAS __attribute__((address_space(3)))
; __device__ __forceinline__ void phase_ln2(const Args& a, LAS unsigned char* lds, const WCtx& w, int l, int nrows) {
;     ...
; #pragma unroll
;         for (int j = 0; j < 4; ++j) mo[j] = mo[j] * (1.0f / 64.0f);
;         if (nrow < r1) { row_load(X + (size_t)nrow * 1024, w.lane, xn); nslot = SLOT[(size_t)nrow * 16 + (w.lane & 15)]; }
;         asm volatile("" ::: "memory");
;         const LAS float* bv = BV + ((row_batch(row) != b_lo) ? 3 * 1024 : 0);
; #pragma unroll
;         for (int j = 0; j < 4; ++j) x[j] = x[j] * ALPHA + *(const LAS f32x4*)(bv + 4 * w.lane + 256 * j) * mo[j];
;         float mean, rstd; ln_stats(x, mean, rstd);
; #pragma unroll
;         for (int j = 0; j < 4; ++j) x[j] = (x[j] - mean) * rstd * *(const LAS f32x4*)(LNG + 4 * w.lane + 256 * j) + *(const LAS f32x4*)(LNB + 4 * w.lane + 256 * j);
.LBB0_2567:
	s_mov_b32 s0, 0x3c800000
	v_pk_mul_f32 v[66:67], v[66:67], s[0:1] op_sel_hi:[1,0]
	v_pk_mul_f32 v[64:65], v[64:65], s[0:1] op_sel_hi:[1,0]
	v_pk_mul_f32 v[62:63], v[62:63], s[0:1] op_sel_hi:[1,0]
	v_pk_mul_f32 v[70:71], v[60:61], s[0:1] op_sel_hi:[1,0]
	v_pk_mul_f32 v[58:59], v[58:59], s[0:1] op_sel_hi:[1,0]
	v_pk_mul_f32 v[56:57], v[56:57], s[0:1] op_sel_hi:[1,0]
	v_pk_mul_f32 v[72:73], v[54:55], s[0:1] op_sel_hi:[1,0]
	v_pk_mul_f32 v[74:75], v[52:53], s[0:1] op_sel_hi:[1,0]
	s_min_i32 s0, s4, 0x8000
	s_ashr_i32 s0, s0, 11
	s_cmp_eq_u32 s0, s21
	s_cselect_b32 s0, 0, 0x3000
	v_add_u32_e32 v60, s0, v68
	ds_read_b128 v[52:55], v60 offset:8192
	s_mov_b32 s0, 0x3fd744fd
	s_waitcnt lgkmcnt(0)
	v_pk_mul_f32 v[54:55], v[64:65], v[54:55]
	v_pk_mul_f32 v[52:53], v[66:67], v[52:53]
	v_pk_fma_f32 v[32:33], v[32:33], s[0:1], v[54:55] op_sel_hi:[1,0,1]
	v_pk_fma_f32 v[30:31], v[30:31], s[0:1], v[52:53] op_sel_hi:[1,0,1]
	ds_read_b128 v[52:55], v60 offset:9216
	s_waitcnt lgkmcnt(0)
	v_pk_mul_f32 v[54:55], v[70:71], v[54:55]
	v_pk_mul_f32 v[52:53], v[62:63], v[52:53]
	v_pk_fma_f32 v[54:55], v[28:29], s[0:1], v[54:55] op_sel_hi:[1,0,1]
	v_pk_fma_f32 v[52:53], v[26:27], s[0:1], v[52:53] op_sel_hi:[1,0,1]
	ds_read_b128 v[26:29], v60 offset:10240
	s_waitcnt lgkmcnt(0)
	v_pk_mul_f32 v[28:29], v[56:57], v[28:29]
	v_pk_mul_f32 v[56:57], v[58:59], v[26:27]
	v_pk_fma_f32 v[26:27], v[24:25], s[0:1], v[28:29] op_sel_hi:[1,0,1]
	v_pk_fma_f32 v[28:29], v[22:23], s[0:1], v[56:57] op_sel_hi:[1,0,1]
	ds_read_b128 v[22:25], v60 offset:11264
	s_waitcnt lgkmcnt(0)
	v_pk_mul_f32 v[22:23], v[72:73], v[22:23]
	v_pk_mul_f32 v[24:25], v[74:75], v[24:25]
	v_pk_fma_f32 v[58:59], v[18:19], s[0:1], v[22:23] op_sel_hi:[1,0,1]
	v_add_f32_e32 v18, v30, v31
	v_add_f32_e32 v19, v32, v33
	v_pk_fma_f32 v[56:57], v[20:21], s[0:1], v[24:25] op_sel_hi:[1,0,1]
	v_add_f32_e32 v18, v18, v19
	v_add_f32_e32 v19, v52, v53
	v_add_f32_e32 v20, v54, v55
	v_add_f32_e32 v18, 0, v18
	v_add_f32_e32 v19, v19, v20
	v_add_f32_e32 v18, v19, v18
	v_add_f32_e32 v19, v28, v29
	v_add_f32_e32 v20, v26, v27
	v_add_f32_e32 v19, v19, v20
	v_add_f32_e32 v18, v19, v18
	v_add_f32_e32 v19, v58, v59
	v_add_f32_e32 v20, v56, v57
	v_add_f32_e32 v19, v19, v20
	v_add_f32_e32 v18, v19, v18
	s_mov_b32 s0, 0xf800000
	s_nop 0
	v_add_f32_dpp v18, v18, v18 quad_perm:[1,0,3,2] row_mask:0xf bank_mask:0xf bound_ctrl:1
	s_nop 1
	v_add_f32_dpp v18, v18, v18 quad_perm:[2,3,0,1] row_mask:0xf bank_mask:0xf bound_ctrl:1
	s_nop 1
	v_add_f32_dpp v18, v18, v18 row_half_mirror row_mask:0xf bank_mask:0xf bound_ctrl:1
	s_nop 1
	v_add_f32_dpp v18, v18, v18 row_mirror row_mask:0xf bank_mask:0xf bound_ctrl:1
	v_mov_b32_e32 v19, v18
	s_nop 1
	v_permlane16_swap_b32_e32 v18, v19
	v_add_f32_e32 v18, v18, v19
	v_mov_b32_e32 v19, v18
	s_nop 1
	v_permlane32_swap_b32_e32 v18, v19
	v_add_f32_e32 v18, v18, v19
	v_fmac_f32_e32 v33, 0xba800000, v18
	v_fmac_f32_e32 v31, 0xba800000, v18
	v_fmamk_f32 v32, v18, 0xba800000, v32
	v_fmamk_f32 v30, v18, 0xba800000, v30
	v_mul_f32_e32 v19, v31, v31
	v_mul_f32_e32 v20, v33, v33
	v_fmac_f32_e32 v19, v30, v30
	v_fmac_f32_e32 v20, v32, v32
	v_fmac_f32_e32 v55, 0xba800000, v18
	v_fmac_f32_e32 v53, 0xba800000, v18
	v_add_f32_e32 v19, v19, v20
	v_fmamk_f32 v54, v18, 0xba800000, v54
	v_fmamk_f32 v52, v18, 0xba800000, v52
	v_mul_f32_e32 v20, v53, v53
	v_mul_f32_e32 v21, v55, v55
	v_fmac_f32_e32 v20, v52, v52
	v_fmac_f32_e32 v21, v54, v54
	v_add_f32_e32 v20, v20, v21
	v_fmac_f32_e32 v27, 0xba800000, v18
	v_fmac_f32_e32 v29, 0xba800000, v18
	v_add_f32_e32 v19, v19, v20
	v_fmamk_f32 v26, v18, 0xba800000, v26
	v_fmamk_f32 v28, v18, 0xba800000, v28
	v_mul_f32_e32 v20, v29, v29
	v_mul_f32_e32 v21, v27, v27
	v_fmac_f32_e32 v20, v28, v28
	v_fmac_f32_e32 v21, v26, v26
	v_add_f32_e32 v20, v20, v21
	v_fmac_f32_e32 v57, 0xba800000, v18
	v_fmac_f32_e32 v59, 0xba800000, v18
	v_add_f32_e32 v19, v20, v19
	v_fmamk_f32 v56, v18, 0xba800000, v56
	v_fmamk_f32 v58, v18, 0xba800000, v58
	v_mul_f32_e32 v18, v59, v59
	v_mul_f32_e32 v20, v57, v57
	v_fmac_f32_e32 v18, v58, v58
	v_fmac_f32_e32 v20, v56, v56
	v_add_f32_e32 v18, v18, v20
	v_add_f32_e32 v18, v18, v19
	s_nop 1
	v_add_f32_dpp v18, v18, v18 quad_perm:[1,0,3,2] row_mask:0xf bank_mask:0xf bound_ctrl:1
	s_nop 1
	v_add_f32_dpp v18, v18, v18 quad_perm:[2,3,0,1] row_mask:0xf bank_mask:0xf bound_ctrl:1
	s_nop 1
	v_add_f32_dpp v18, v18, v18 row_half_mirror row_mask:0xf bank_mask:0xf bound_ctrl:1
	s_nop 1
	v_add_f32_dpp v18, v18, v18 row_mirror row_mask:0xf bank_mask:0xf bound_ctrl:1
	v_mov_b32_e32 v19, v18
	s_nop 1
	v_permlane16_swap_b32_e32 v18, v19
	v_add_f32_e32 v18, v18, v19
	v_mov_b32_e32 v19, v18
	s_nop 1
	v_permlane32_swap_b32_e32 v18, v19
	v_add_f32_e32 v18, v18, v19
	v_fmamk_f32 v18, v18, 0x3a800000, v251
	v_cmp_gt_f32_e32 vcc, s0, v18
	v_mul_f32_e32 v19, 0x4f800000, v18
	s_nop 0
	v_cndmask_b32_e32 v18, v18, v19, vcc
	v_sqrt_f32_e32 v19, v18
	s_nop 0
	v_add_u32_e32 v20, -1, v19
	v_fma_f32 v21, -v20, v19, v18
	v_cmp_ge_f32_e64 s[0:1], 0, v21
	v_add_u32_e32 v21, 1, v19
	s_nop 0
	v_cndmask_b32_e64 v20, v19, v20, s[0:1]
	v_fma_f32 v19, -v21, v19, v18
	v_cmp_lt_f32_e64 s[0:1], 0, v19
	s_nop 1
	v_cndmask_b32_e64 v19, v20, v21, s[0:1]
	v_mul_f32_e32 v20, 0x37800000, v19
	v_cndmask_b32_e32 v19, v19, v20, vcc
	v_cmp_class_f32_e32 vcc, v18, v230
	s_nop 1
	v_cndmask_b32_e32 v18, v19, v18, vcc
	v_div_scale_f32 v19, s[0:1], v18, v18, 1.0
	v_rcp_f32_e32 v20, v19
	s_mov_b64 s[0:1], -1
	v_fma_f32 v21, -v19, v20, 1.0
	v_fmac_f32_e32 v20, v21, v20
	v_div_scale_f32 v21, vcc, 1.0, v18, 1.0
	v_mul_f32_e32 v22, v21, v20
	v_fma_f32 v23, -v19, v22, v21
	v_fmac_f32_e32 v22, v23, v20
	v_fma_f32 v19, -v19, v22, v21
	v_div_fmas_f32 v19, v19, v20, v22
	v_div_fixup_f32 v50, v19, v18, 1.0
	ds_read_b128 v[18:21], v68
	ds_read_b128 v[22:25], v68 offset:4096
	v_pk_mul_f32 v[30:31], v[30:31], v[50:51] op_sel_hi:[1,0]
	v_pk_mul_f32 v[32:33], v[32:33], v[50:51] op_sel_hi:[1,0]
	v_pk_mul_f32 v[52:53], v[52:53], v[50:51] op_sel_hi:[1,0]
	v_pk_mul_f32 v[54:55], v[54:55], v[50:51] op_sel_hi:[1,0]
	s_waitcnt lgkmcnt(0)
; #define LAS __attribute__((address_space(3)))
; __device__ __forceinline__ void phase_ln2(const Args& a, LAS unsigned char* lds, const WCtx& w, int l, int nrows) {
;     ...
;         for (int j = 0; j < 4; ++j) x[j] = (x[j] - mean) * rstd * *(const LAS f32x4*)(LNG + 4 * w.lane + 256 * j) + *(const LAS f32x4*)(LNB + 4 * w.lane + 256 * j);
;         if (l == DEPTH - 1) row_store(a.out + (size_t)row * 1024, w.lane, x);
;         else { row_store(X + (size_t)row * 1024, w.lane, x);
;             ln_stats(x, mean, rstd); bf16* hrow = H + (size_t)row * 1024;
; #pragma unroll
;             for (int j = 0; j < 4; ++j) { const f32x4 sh = *(const LAS f32x4*)(bv + 1024 + 4 * w.lane + 256 * j), sc = *(const LAS f32x4*)(bv + 2048 + 4 * w.lane + 256 * j);
	v_pk_fma_f32 v[20:21], v[20:21], v[32:33], v[24:25]
	v_pk_fma_f32 v[18:19], v[18:19], v[30:31], v[22:23]
	ds_read_b128 v[22:25], v68 offset:1024
	ds_read_b128 v[30:33], v68 offset:5120
	v_pk_mul_f32 v[58:59], v[58:59], v[50:51] op_sel_hi:[1,0]
	v_pk_mul_f32 v[56:57], v[56:57], v[50:51] op_sel_hi:[1,0]
	s_and_b64 vcc, exec, s[44:45]
	s_waitcnt lgkmcnt(0)
	v_pk_fma_f32 v[24:25], v[24:25], v[54:55], v[32:33]
	v_pk_fma_f32 v[22:23], v[22:23], v[52:53], v[30:31]
	v_pk_mul_f32 v[52:53], v[28:29], v[50:51] op_sel_hi:[1,0]
	v_pk_mul_f32 v[54:55], v[26:27], v[50:51] op_sel_hi:[1,0]
	ds_read_b128 v[26:29], v68 offset:2048
	ds_read_b128 v[30:33], v68 offset:6144
	s_waitcnt lgkmcnt(0)
	v_pk_fma_f32 v[28:29], v[28:29], v[54:55], v[32:33]
	v_pk_fma_f32 v[26:27], v[26:27], v[52:53], v[30:31]
	ds_read_b128 v[30:33], v68 offset:3072
	ds_read_b128 v[52:55], v68 offset:7168
	s_waitcnt lgkmcnt(0)
	v_pk_fma_f32 v[32:33], v[32:33], v[56:57], v[54:55]
	v_pk_fma_f32 v[30:31], v[30:31], v[58:59], v[52:53]
	s_cbranch_vccz .LBB0_2569
	s_ashr_i32 s5, s4, 31
	s_lshl_b64 s[0:1], s[4:5], 12
	v_lshl_add_u64 v[52:53], v[36:37], 0, s[0:1]
	global_store_dwordx4 v[52:53], v[18:21], off
	global_store_dwordx4 v[52:53], v[22:25], off offset:1024
	global_store_dwordx4 v[52:53], v[26:29], off offset:2048
	global_store_dwordx4 v[52:53], v[30:33], off offset:3072
	v_add_f32_e32 v50, v18, v19
	v_add_f32_e32 v52, v20, v21
	v_add_f32_e32 v50, v50, v52
	v_add_f32_e32 v52, v22, v23
	v_add_f32_e32 v53, v24, v25
	v_add_f32_e32 v50, 0, v50
	v_add_f32_e32 v52, v52, v53
	v_add_f32_e32 v50, v52, v50
	v_add_f32_e32 v52, v26, v27
	v_add_f32_e32 v53, v28, v29
	v_add_f32_e32 v52, v52, v53
	v_add_f32_e32 v50, v52, v50
	v_add_f32_e32 v52, v30, v31
	v_add_f32_e32 v53, v32, v33
	v_add_f32_e32 v52, v52, v53
	v_add_f32_e32 v50, v52, v50
	v_mov_b32_e32 v67, v21
	v_mov_b32_e32 v75, v19
	v_add_f32_dpp v50, v50, v50 quad_perm:[1,0,3,2] row_mask:0xf bank_mask:0xf bound_ctrl:1
	v_mov_b32_e32 v77, v25
	v_mov_b32_e32 v79, v23
	v_add_f32_dpp v50, v50, v50 quad_perm:[2,3,0,1] row_mask:0xf bank_mask:0xf bound_ctrl:1
	v_mov_b32_e32 v57, v29
	v_mov_b32_e32 v59, v27
	v_add_f32_dpp v50, v50, v50 row_half_mirror row_mask:0xf bank_mask:0xf bound_ctrl:1
	v_mov_b32_e32 v55, v31
	s_mov_b32 s0, 0xf800000
	v_add_f32_dpp v50, v50, v50 row_mirror row_mask:0xf bank_mask:0xf bound_ctrl:1
	v_mov_b32_e32 v52, v50
	s_nop 1
	v_permlane16_swap_b32_e32 v50, v52
	v_add_f32_e32 v50, v50, v52
	v_mov_b32_e32 v52, v50
	s_nop 1
	v_permlane32_swap_b32_e32 v50, v52
	v_add_f32_e32 v50, v50, v52
	v_fmac_f32_e32 v67, 0xba800000, v50
	v_fmac_f32_e32 v75, 0xba800000, v50
	v_fmamk_f32 v66, v50, 0xba800000, v20
	v_fmamk_f32 v74, v50, 0xba800000, v18
	v_mul_f32_e32 v52, v75, v75
	v_mul_f32_e32 v53, v67, v67
	v_fmac_f32_e32 v52, v74, v74
	v_fmac_f32_e32 v53, v66, v66
	v_fmac_f32_e32 v77, 0xba800000, v50
	v_fmac_f32_e32 v79, 0xba800000, v50
	v_add_f32_e32 v52, v52, v53
	v_fmamk_f32 v76, v50, 0xba800000, v24
	v_fmamk_f32 v78, v50, 0xba800000, v22
	v_mul_f32_e32 v53, v79, v79
	v_mul_f32_e32 v54, v77, v77
	v_fmac_f32_e32 v53, v78, v78
	v_fmac_f32_e32 v54, v76, v76
	v_add_f32_e32 v53, v53, v54
	v_fmac_f32_e32 v57, 0xba800000, v50
	v_fmac_f32_e32 v59, 0xba800000, v50
	v_add_f32_e32 v52, v52, v53
	v_fmamk_f32 v56, v50, 0xba800000, v28
	v_fmamk_f32 v58, v50, 0xba800000, v26
	v_mul_f32_e32 v53, v59, v59
	v_mul_f32_e32 v54, v57, v57
	v_fmac_f32_e32 v53, v58, v58
	v_fmac_f32_e32 v54, v56, v56
	v_add_f32_e32 v53, v53, v54
	v_add_f32_e32 v61, v53, v52
	v_mov_b32_e32 v53, v33
	v_fmac_f32_e32 v53, 0xba800000, v50
	v_fmac_f32_e32 v55, 0xba800000, v50
	v_fmamk_f32 v52, v50, 0xba800000, v32
	v_fmamk_f32 v54, v50, 0xba800000, v30
	v_mul_f32_e32 v50, v55, v55
	v_mul_f32_e32 v62, v53, v53
	v_fmac_f32_e32 v50, v54, v54
	v_fmac_f32_e32 v62, v52, v52
	v_add_f32_e32 v50, v50, v62
	v_add_f32_e32 v50, v50, v61
	s_lshl_b64 s[8:9], s[4:5], 10
	s_nop 0
	v_add_f32_dpp v50, v50, v50 quad_perm:[1,0,3,2] row_mask:0xf bank_mask:0xf bound_ctrl:1
	s_nop 1
	v_add_f32_dpp v50, v50, v50 quad_perm:[2,3,0,1] row_mask:0xf bank_mask:0xf bound_ctrl:1
	s_nop 1
	v_add_f32_dpp v50, v50, v50 row_half_mirror row_mask:0xf bank_mask:0xf bound_ctrl:1
	s_nop 1
	v_add_f32_dpp v50, v50, v50 row_mirror row_mask:0xf bank_mask:0xf bound_ctrl:1
	v_mov_b32_e32 v61, v50
	s_nop 1
	v_permlane16_swap_b32_e32 v50, v61
	v_add_f32_e32 v50, v50, v61
	v_mov_b32_e32 v61, v50
	s_nop 1
	v_permlane32_swap_b32_e32 v50, v61
	v_add_f32_e32 v50, v50, v61
	v_fmamk_f32 v50, v50, 0x3a800000, v251
	v_cmp_gt_f32_e32 vcc, s0, v50
	v_mul_f32_e32 v61, 0x4f800000, v50
	s_nop 0
	v_cndmask_b32_e32 v50, v50, v61, vcc
	v_sqrt_f32_e32 v61, v50
	s_nop 0
	v_add_u32_e32 v62, -1, v61
	v_fma_f32 v63, -v62, v61, v50
	v_cmp_ge_f32_e64 s[0:1], 0, v63
	v_add_u32_e32 v63, 1, v61
	s_nop 0
	v_cndmask_b32_e64 v62, v61, v62, s[0:1]
	v_fma_f32 v61, -v63, v61, v50
	v_cmp_lt_f32_e64 s[0:1], 0, v61
	s_nop 1
	v_cndmask_b32_e64 v61, v62, v63, s[0:1]
	v_mul_f32_e32 v62, 0x37800000, v61
	v_cndmask_b32_e32 v61, v61, v62, vcc
	v_cmp_class_f32_e32 vcc, v50, v230
	s_nop 1
	v_cndmask_b32_e32 v50, v61, v50, vcc
	v_div_scale_f32 v61, s[0:1], v50, v50, 1.0
	v_rcp_f32_e32 v62, v61
	s_lshl_b64 s[0:1], s[4:5], 11
	v_fma_f32 v63, -v61, v62, 1.0
	v_fmac_f32_e32 v62, v63, v62
	v_div_scale_f32 v63, vcc, 1.0, v50, 1.0
	v_mul_f32_e32 v64, v63, v62
	v_fma_f32 v65, -v61, v64, v63
	v_fmac_f32_e32 v64, v65, v62
	v_fma_f32 v61, -v61, v64, v63
	v_div_fmas_f32 v61, v61, v62, v64
	ds_read_b128 v[62:65], v60 offset:12288
	ds_read_b128 v[70:73], v60 offset:16384
	v_div_fixup_f32 v50, v61, v50, 1.0
	v_pk_mul_f32 v[74:75], v[74:75], v[50:51] op_sel_hi:[1,0]
	v_pk_mul_f32 v[66:67], v[66:67], v[50:51] op_sel_hi:[1,0]
	v_pk_mul_f32 v[76:77], v[76:77], v[50:51] op_sel_hi:[1,0]
	s_waitcnt lgkmcnt(0)
; #define LAS __attribute__((address_space(3)))
; __device__ __forceinline__ unsigned cvt_pk_bf16(float lo, float hi) { unsigned r; asm volatile("v_cvt_pk_bf16_f32 %0, %1, %2" : "=v"(r) : "v"(lo), "v"(hi)); return r; }
; __device__ __forceinline__ unsigned pk4c_fp8(f32x4 v) { return pk4_fp8(fminf(fmaxf(v[0], -448.f), 448.f), fminf(fmaxf(v[1], -448.f), 448.f), fminf(fmaxf(v[2], -448.f), 448.f), fminf(fmaxf(v[3], -448.f), 448.f)); }
; __device__ __forceinline__ void phase_ln2(const Args& a, LAS unsigned char* lds, const WCtx& w, int l, int nrows) {
;     ...
;         if (l == DEPTH - 1) row_store(a.out + (size_t)row * 1024, w.lane, x);
;         else { row_store(X + (size_t)row * 1024, w.lane, x);
;             ln_stats(x, mean, rstd); bf16* hrow = H + (size_t)row * 1024;
; #pragma unroll
;             for (int j = 0; j < 4; ++j) { const f32x4 sh = *(const LAS f32x4*)(bv + 1024 + 4 * w.lane + 256 * j), sc = *(const LAS f32x4*)(bv + 2048 + 4 * w.lane + 256 * j);
;                 const f32x4 hv = (x[j] - mean) * rstd * (sc + 1.0f) + sh;
;                 v2u wv; wv.x = cvt_pk_bf16(hv[0], hv[1]); wv.y = cvt_pk_bf16(hv[2], hv[3]); *((v2u*)hrow + w.lane + 64 * j) = wv;
;                 ((unsigned*)(a.ws + WS_H8 + (size_t)row * 1024))[w.lane + 64 * j] = pk4c_fp8(hv); } }
	v_pk_add_f32 v[72:73], v[72:73], 1.0 op_sel_hi:[1,0]
	v_pk_add_f32 v[70:71], v[70:71], 1.0 op_sel_hi:[1,0]
	v_pk_fma_f32 v[64:65], v[72:73], v[66:67], v[64:65]
	v_pk_fma_f32 v[62:63], v[70:71], v[74:75], v[62:63]
	v_lshl_add_u64 v[74:75], v[40:41], 0, s[0:1]
	s_mov_b32 s1, 0xc3e00000
	v_cvt_pk_bf16_f32 v66, v62, v63
	v_cvt_pk_bf16_f32 v67, v64, v65
	v_med3_f32 v61, v62, s1, v236
	v_med3_f32 v62, v63, s1, v236
	v_med3_f32 v63, v64, s1, v236
	v_med3_f32 v64, v65, s1, v236
	v_mov_b32_e32 v65, v51
	v_cvt_pk_fp8_f32 v65, v61, v62
	global_store_dwordx2 v[74:75], v[66:67], off
	v_pk_mul_f32 v[66:67], v[78:79], v[50:51] op_sel_hi:[1,0]
	s_mov_b32 s0, 0x46000000
	v_cvt_pk_fp8_f32 v65, v63, v64 op_sel:[0,0,1]
	v_lshl_add_u64 v[62:63], v[48:49], 0, s[8:9]
	v_pk_mul_f32 v[58:59], v[58:59], v[50:51] op_sel_hi:[1,0]
	v_pk_mul_f32 v[56:57], v[56:57], v[50:51] op_sel_hi:[1,0]
	global_store_dword v[62:63], v65, off
	ds_read_b128 v[62:65], v60 offset:13312
	ds_read_b128 v[70:73], v60 offset:17408
	v_pk_mul_f32 v[54:55], v[54:55], v[50:51] op_sel_hi:[1,0]
	v_pk_mul_f32 v[52:53], v[52:53], v[50:51] op_sel_hi:[1,0]
	s_waitcnt lgkmcnt(0)
	v_pk_add_f32 v[72:73], v[72:73], 1.0 op_sel_hi:[1,0]
	v_pk_add_f32 v[70:71], v[70:71], 1.0 op_sel_hi:[1,0]
	v_pk_fma_f32 v[64:65], v[76:77], v[72:73], v[64:65]
	v_pk_fma_f32 v[62:63], v[66:67], v[70:71], v[62:63]
	s_nop 0
	v_cvt_pk_bf16_f32 v66, v62, v63
	v_cvt_pk_bf16_f32 v67, v64, v65
	v_med3_f32 v61, v62, s1, v236
	v_med3_f32 v62, v63, s1, v236
	v_med3_f32 v63, v64, s1, v236
	v_med3_f32 v64, v65, s1, v236
	v_mov_b32_e32 v65, v51
	v_cvt_pk_fp8_f32 v65, v61, v62
	global_store_dwordx2 v[74:75], v[66:67], off offset:512
	v_mov_b32_e32 v61, v51
	v_cvt_pk_fp8_f32 v65, v63, v64 op_sel:[0,0,1]
	v_lshl_add_u64 v[62:63], v[42:43], 0, s[8:9]
	v_add_co_u32_e32 v66, vcc, s0, v62
	s_nop 1
	v_addc_co_u32_e32 v67, vcc, 0, v63, vcc
	global_store_dword v[66:67], v65, off offset:256
	ds_read_b128 v[62:65], v60 offset:14336
	ds_read_b128 v[70:73], v60 offset:18432
	s_waitcnt lgkmcnt(0)
	v_pk_add_f32 v[70:71], v[70:71], 1.0 op_sel_hi:[1,0]
	s_nop 0
	v_pk_fma_f32 v[58:59], v[58:59], v[70:71], v[62:63]
	v_pk_add_f32 v[72:73], v[72:73], 1.0 op_sel_hi:[1,0]
	v_cvt_pk_bf16_f32 v62, v58, v59
	v_med3_f32 v58, v58, s1, v236
	v_med3_f32 v59, v59, s1, v236
	v_cvt_pk_fp8_f32 v61, v58, v59
	v_pk_fma_f32 v[56:57], v[56:57], v[72:73], v[64:65]
	s_nop 0
	v_cvt_pk_bf16_f32 v63, v56, v57
	v_med3_f32 v56, v56, s1, v236
	v_med3_f32 v57, v57, s1, v236
	v_cvt_pk_fp8_f32 v61, v56, v57 op_sel:[0,0,1]
	global_store_dwordx2 v[74:75], v[62:63], off offset:1024
	global_store_dword v[66:67], v61, off offset:512
	ds_read_b128 v[56:59], v60 offset:15360
	ds_read_b128 v[60:63], v60 offset:19456
	s_waitcnt lgkmcnt(0)
	v_pk_add_f32 v[60:61], v[60:61], 1.0 op_sel_hi:[1,0]
	s_nop 0
	v_pk_fma_f32 v[54:55], v[54:55], v[60:61], v[56:57]
	v_pk_add_f32 v[62:63], v[62:63], 1.0 op_sel_hi:[1,0]
	v_cvt_pk_bf16_f32 v56, v54, v55
	v_med3_f32 v50, v54, s1, v236
	v_med3_f32 v54, v55, s1, v236
	v_mov_b32_e32 v55, v51
	v_cvt_pk_fp8_f32 v55, v50, v54
	v_pk_fma_f32 v[52:53], v[52:53], v[62:63], v[58:59]
	s_nop 0
	v_cvt_pk_bf16_f32 v57, v52, v53
	v_med3_f32 v52, v52, s1, v236
	v_med3_f32 v53, v53, s1, v236
	v_cvt_pk_fp8_f32 v55, v52, v53 op_sel:[0,0,1]
	global_store_dwordx2 v[74:75], v[56:57], off offset:1536
	s_mov_b64 s[0:1], 0
	global_store_dword v[66:67], v55, off offset:768
	s_andn2_b64 vcc, exec, s[0:1]
	s_cbranch_vccnz .Lm_latch12
	s_ashr_i32 s5, s4, 31
	s_lshl_b64 s[0:1], s[4:5], 12
	v_lshl_add_u64 v[52:53], v[44:45], 0, s[0:1]
	global_store_dwordx4 v[52:53], v[18:21], off
	global_store_dwordx4 v[52:53], v[22:25], off offset:1024
	global_store_dwordx4 v[52:53], v[26:29], off offset:2048
	global_store_dwordx4 v[52:53], v[30:33], off offset:3072
	s_branch .Lm_latch16
